# baseline (speedup 1.0000x reference)
; template <int EPI> ...
;     ...
;       unsigned long long sqc[8];
; #pragma unroll
;       for (int m = 0; m < 8; ++m) sqc[m] = ssq_in[pm * 256 + wr * 128 + fr + m * 16];
; #pragma unroll
;       for (int m = 0; m < 8; ++m) rs[m] = rsqrtf((float)sqc[m] * SSQ_UNFIX + 1e-6f);
;     ...
;       const bool gate = (EPI == EPI_PROJ) && (bcol >= 2304);
;       const bool sbv = (EPI == EPI_PROJ) && ((bcol == 1024) || (bcol == 1280));
;       const bool swv = (EPI == EPI_PROJ) && (bcol == 2048) && (wc >= 2);
;       if (sbv || swv) {
.LBB0_145:
	s_waitcnt vmcnt(0)
	v_cvt_f32_u32_e32 v151, v151
	v_cvt_f32_u32_e32 v150, v150
	v_fmamk_f32 v150, v151, 0x4f800000, v150
	v_fmamk_f32 v150, v150, 0x30800000, v160
	v_rsq_f32_e32 v150, v150
	v_cvt_f32_u32_e32 v149, v149
	v_cvt_f32_u32_e32 v148, v148
	v_fmamk_f32 v148, v149, 0x4f800000, v148
	v_fmamk_f32 v148, v148, 0x30800000, v160
	v_rsq_f32_e32 v148, v148
	v_cvt_f32_u32_e32 v147, v147
	v_cvt_f32_u32_e32 v146, v146
	v_fmamk_f32 v146, v147, 0x4f800000, v146
	v_fmamk_f32 v146, v146, 0x30800000, v160
	v_rsq_f32_e32 v146, v146
	s_nop 0
	v_cvt_f32_u32_e32 v145, v145
	v_cvt_f32_u32_e32 v144, v144
	v_fmamk_f32 v144, v145, 0x4f800000, v144
	v_fmamk_f32 v144, v144, 0x30800000, v160
	v_rsq_f32_e32 v144, v144
	v_mov_b32_e32 v149, v3
	v_cvt_f32_u32_e32 v143, v143
	v_cvt_f32_u32_e32 v142, v142
	v_fmamk_f32 v142, v143, 0x4f800000, v142
	v_fmamk_f32 v142, v142, 0x30800000, v160
	v_rsq_f32_e32 v142, v142
	s_nop 0
	v_cvt_f32_u32_e32 v141, v141
	v_cvt_f32_u32_e32 v140, v140
	v_fmamk_f32 v140, v141, 0x4f800000, v140
	v_fmamk_f32 v140, v140, 0x30800000, v160
	v_rsq_f32_e32 v140, v140
	v_and_b32_e32 v147, 15, v149
	v_cvt_f32_u32_e32 v139, v139
	v_cvt_f32_u32_e32 v138, v138
	v_fmamk_f32 v138, v139, 0x4f800000, v138
	v_fmamk_f32 v138, v138, 0x30800000, v160
	v_rsq_f32_e32 v138, v138
	v_cvt_f32_u32_e32 v137, v137
	v_cvt_f32_u32_e32 v136, v136
	v_fmamk_f32 v136, v137, 0x4f800000, v136
	v_fmamk_f32 v136, v136, 0x30800000, v160
	v_rsq_f32_e32 v136, v136
	v_bfe_u32 v145, v149, 4, 2
	s_lshl_b32 s6, s51, 8
	v_ashrrev_i32_e32 v139, 1, v149
	s_and_b32 s4, s51, -2
	v_ashrrev_i32_e32 v137, 6, v149
	v_and_b32_e32 v139, 0xffffff80, v139
	s_cmp_lg_u32 s4, 4
	v_and_b32_e32 v143, 3, v137
	v_add_u32_e32 v139, s16, v139
	s_cselect_b64 s[16:17], -1, 0
	s_cmp_lg_u32 s51, 8
	s_cselect_b64 s[4:5], -1, 0
	v_cmp_gt_u32_e32 vcc, 2, v143
	s_or_b64 s[4:5], s[4:5], vcc
	v_lshl_add_u32 v137, v137, 13, v169
	v_lshlrev_b32_e32 v141, 6, v143
	s_and_b64 s[4:5], s[16:17], s[4:5]
	s_and_saveexec_b64 s[22:23], s[4:5]
	s_xor_b64 s[22:23], exec, s[22:23]
	s_cbranch_execz .LBB0_275
	s_cmp_lt_i32 s51, 9
	s_cselect_b64 s[24:25], -1, 0
	s_cmp_gt_i32 s51, 8
	v_pk_mul_f32 v[134:135], v[134:135], v[150:151] op_sel_hi:[1,0]
	v_pk_mul_f32 v[132:133], v[132:133], v[150:151] op_sel_hi:[1,0]
	s_mov_b64 s[4:5], -1
	s_cbranch_scc1 .LBB0_148
	s_mov_b64 s[4:5], 0

;   __device__ __forceinline__ u16* proj() const { return (u16*)(ws + 185 * MB); }
; template <int EPI> ...
;     ...
;       unsigned long long sqc[8];
; #pragma unroll
;       for (int m = 0; m < 8; ++m) sqc[m] = ssq_in[pm * 256 + wr * 128 + fr + m * 16];
; #pragma unroll
;       for (int m = 0; m < 8; ++m) rs[m] = rsqrtf((float)sqc[m] * SSQ_UNFIX + 1e-6f);
;     ...
;         const int ld = (EPI == EPI_PROJ) ? INW : DFF;
;         u16* gout = p.proj() + (long)(brow + wr * 128 + (lane >> 3)) * ld + bcol + wc * 64 + (lane & 7) * 8;
;         const int wswz = fr & 7, rswz = (lane >> 3) & 7;
; #pragma unroll
;         for (int h = 0; h < 2; ++h) {
; #pragma unroll
;           for (int mm = 0; mm < 4; ++mm)
; #pragma unroll
;             for (int n = 0; n < 4; ++n) {
;               f32x4 v = acc[h * 4 + mm][n] * rs[h * 4 + mm];
;               if constexpr (EPI == EPI_PROJ) {
;                 if (gate) {
; #pragma unroll
;                   for (int j = 0; j < 4; ++j) v[j] = __builtin_amdgcn_rcpf(1.0f + __expf(-v[j]));
;                 }
;               } else {
; #pragma unroll
;                 for (int j = 0; j < 4; ++j) { float r = fmaxf(v[j], 0.f); v[j] = r * r; }
;               }
;               u32x2 o = {pack2(v[0], v[1]), pack2(v[2], v[3])};
;               *(u32x2*)(wst + (mm * 16 + fr) * 128 + (((n * 2 + (fq >> 1)) ^ wswz) << 4) + (fq & 1) * 8) = o;
.LBB0_674:
	s_waitcnt vmcnt(0)
	v_cvt_f32_u32_e32 v151, v151
	v_cvt_f32_u32_e32 v150, v150
	v_fmamk_f32 v150, v151, 0x4f800000, v150
	v_fmamk_f32 v150, v150, 0x30800000, v160
	v_rsq_f32_e32 v152, v150
	s_lshl_b32 s20, s92, 8
	s_ashr_i32 s21, s20, 31
	v_mov_b32_e32 v157, v2
	s_mov_b32 s26, s75
	s_mov_b64 s[24:25], s[14:15]
	s_mov_b32 s92, s91
	v_cvt_f32_u32_e32 v149, v149
	v_cvt_f32_u32_e32 v148, v148
	v_fmamk_f32 v148, v149, 0x4f800000, v148
	v_fmamk_f32 v148, v148, 0x30800000, v160
	v_rsq_f32_e32 v150, v148
	v_pk_mul_f32 v[134:135], v[134:135], v[152:153] op_sel_hi:[1,0]
	v_pk_mul_f32 v[124:125], v[124:125], v[152:153] op_sel_hi:[1,0]
	v_max_f32_e32 v134, 0, v134
	v_max_f32_e32 v135, 0, v135
	v_pk_mul_f32 v[126:127], v[126:127], v[152:153] op_sel_hi:[1,0]
	v_max_f32_e32 v124, 0, v124
	v_cvt_f32_u32_e32 v147, v147
	v_cvt_f32_u32_e32 v146, v146
	v_fmamk_f32 v146, v147, 0x4f800000, v146
	v_fmamk_f32 v146, v146, 0x30800000, v160
	v_rsq_f32_e32 v148, v146
	v_max_f32_e32 v125, 0, v125
	v_pk_mul_f32 v[134:135], v[134:135], v[134:135]
	v_pk_mul_f32 v[124:125], v[124:125], v[124:125]
	v_max_f32_e32 v126, 0, v126
	v_max_f32_e32 v127, 0, v127
	v_pk_mul_f32 v[126:127], v[126:127], v[126:127]
	v_cvt_f32_u32_e32 v145, v145
	v_cvt_f32_u32_e32 v144, v144
	v_fmamk_f32 v144, v145, 0x4f800000, v144
	v_fmamk_f32 v144, v144, 0x30800000, v160
	v_rsq_f32_e32 v146, v144
	v_pk_mul_f32 v[132:133], v[132:133], v[152:153] op_sel_hi:[1,0]
	v_pk_mul_f32 v[128:129], v[128:129], v[152:153] op_sel_hi:[1,0]
	v_pk_mul_f32 v[120:121], v[120:121], v[152:153] op_sel_hi:[1,0]
	v_max_f32_e32 v132, 0, v132
	v_max_f32_e32 v133, 0, v133
	v_max_f32_e32 v128, 0, v128
	v_cvt_f32_u32_e32 v143, v143
	v_cvt_f32_u32_e32 v142, v142
	v_fmamk_f32 v142, v143, 0x4f800000, v142
	v_fmamk_f32 v142, v142, 0x30800000, v160
	v_rsq_f32_e32 v144, v142
	v_max_f32_e32 v129, 0, v129
	v_pk_mul_f32 v[122:123], v[122:123], v[152:153] op_sel_hi:[1,0]
	v_max_f32_e32 v120, 0, v120
	v_max_f32_e32 v121, 0, v121
	v_pk_mul_f32 v[132:133], v[132:133], v[132:133]
	v_pk_mul_f32 v[128:129], v[128:129], v[128:129]
	v_cvt_f32_u32_e32 v141, v141
	v_cvt_f32_u32_e32 v140, v140
	v_fmamk_f32 v140, v141, 0x4f800000, v140
	v_fmamk_f32 v140, v140, 0x30800000, v160
	v_rsq_f32_e32 v142, v140
	v_pk_mul_f32 v[120:121], v[120:121], v[120:121]
	v_max_f32_e32 v122, 0, v122
	v_max_f32_e32 v123, 0, v123
	v_cvt_pk_bf16_f32 v128, v128, v129
	v_pk_mul_f32 v[122:123], v[122:123], v[122:123]
	s_mov_b32 s93, s90
	v_cvt_f32_u32_e32 v139, v139
	v_cvt_f32_u32_e32 v138, v138
	v_fmamk_f32 v138, v139, 0x4f800000, v138
	v_fmamk_f32 v138, v138, 0x30800000, v160
	v_rsq_f32_e32 v140, v138
	v_mov_b32_e32 v141, v3
	v_bfe_u32 v147, v141, 3, 3
	v_lshrrev_b32_e32 v151, 1, v141
	v_and_b32_e32 v151, 8, v151
	v_and_b32_e32 v145, 0xc0, v141
	v_cvt_f32_u32_e32 v137, v137
	v_cvt_f32_u32_e32 v136, v136
	v_fmamk_f32 v136, v137, 0x4f800000, v136
	v_fmamk_f32 v136, v136, 0x30800000, v160
	v_rsq_f32_e32 v138, v136
	v_lshlrev_b32_e32 v139, 7, v141
	v_bfe_u32 v149, v141, 5, 1
	v_lshlrev_b32_e32 v156, 1, v145
	v_and_b32_e32 v145, 7, v141
	v_pk_mul_f32 v[94:95], v[94:95], v[148:149] op_sel_hi:[1,0]
	v_pk_mul_f32 v[92:93], v[92:93], v[148:149] op_sel_hi:[1,0]
	v_and_b32_e32 v136, 0xffffe000, v139
	v_add_u32_e32 v143, 0x10000, v136
	v_ashrrev_i32_e32 v136, 1, v141
	v_and_b32_e32 v136, 0xffffff80, v136
	v_add_u32_e32 v136, s22, v136
	v_or_b32_e32 v136, v136, v147
	v_ashrrev_i32_e32 v137, 31, v136
	v_and_b32_e32 v139, 0x780, v139
	v_lshlrev_b64 v[136:137], 13, v[136:137]
	v_or3_b32 v151, v143, v139, v151
	v_lshlrev_b32_e32 v139, 7, v147
	v_bitop3_b32 v147, v147, v141, 7 bitop3:0x78
	v_lshl_add_u64 v[136:137], s[38:39], 0, v[136:137]
	v_lshlrev_b32_e32 v147, 4, v147
	v_lshl_add_u64 v[136:137], s[20:21], 1, v[136:137]
	v_pk_mul_f32 v[110:111], v[110:111], v[150:151] op_sel_hi:[1,0]
	v_pk_mul_f32 v[108:109], v[108:109], v[150:151] op_sel_hi:[1,0]
	v_pk_mul_f32 v[78:79], v[78:79], v[146:147] op_sel_hi:[1,0]
	v_pk_mul_f32 v[76:77], v[76:77], v[146:147] op_sel_hi:[1,0]
	v_lshl_add_u64 v[136:137], v[136:137], 0, v[156:157]
	v_lshlrev_b32_e32 v156, 4, v145
	v_max_f32_e32 v108, 0, v108
	v_max_f32_e32 v109, 0, v109
	v_max_f32_e32 v110, 0, v110
	v_max_f32_e32 v111, 0, v111
	v_max_f32_e32 v92, 0, v92
	v_max_f32_e32 v93, 0, v93
	v_max_f32_e32 v94, 0, v94
	v_max_f32_e32 v95, 0, v95
	v_max_f32_e32 v76, 0, v76
	v_max_f32_e32 v77, 0, v77
	v_max_f32_e32 v78, 0, v78
	v_max_f32_e32 v79, 0, v79
	v_lshl_add_u64 v[136:137], v[136:137], 0, v[156:157]
	v_cvt_pk_bf16_f32 v157, v134, v135
	v_cvt_pk_bf16_f32 v134, v124, v125
	v_bitop3_b32 v124, v149, v145, 2 bitop3:0x36
	v_pk_mul_f32 v[108:109], v[108:109], v[108:109]
	v_pk_mul_f32 v[110:111], v[110:111], v[110:111]
	v_pk_mul_f32 v[92:93], v[92:93], v[92:93]
	v_pk_mul_f32 v[94:95], v[94:95], v[94:95]
	v_pk_mul_f32 v[76:77], v[76:77], v[76:77]
	v_pk_mul_f32 v[78:79], v[78:79], v[78:79]
	v_cvt_pk_bf16_f32 v135, v126, v127
	v_lshl_or_b32 v124, v124, 4, v151
	v_pk_mul_f32 v[126:127], v[130:131], v[152:153] op_sel_hi:[1,0]
	v_cvt_pk_bf16_f32 v108, v108, v109
	v_cvt_pk_bf16_f32 v109, v110, v111
	v_cvt_pk_bf16_f32 v92, v92, v93
	v_cvt_pk_bf16_f32 v93, v94, v95
	v_cvt_pk_bf16_f32 v76, v76, v77
	v_cvt_pk_bf16_f32 v77, v78, v79
	v_max_f32_e32 v126, 0, v126
	v_max_f32_e32 v127, 0, v127
	v_pk_mul_f32 v[118:119], v[118:119], v[150:151] op_sel_hi:[1,0]
	v_pk_mul_f32 v[116:117], v[116:117], v[150:151] op_sel_hi:[1,0]
	ds_write2st64_b64 v124, v[134:135], v[108:109] offset1:4
	v_pk_mul_f32 v[108:109], v[114:115], v[150:151] op_sel_hi:[1,0]
	v_pk_mul_f32 v[110:111], v[112:113], v[150:151] op_sel_hi:[1,0]
	v_pk_mul_f32 v[106:107], v[106:107], v[150:151] op_sel_hi:[1,0]
; #define WAIT_V(n) asm volatile("s_waitcnt vmcnt(%0)" ::"n"(n) : "memory")
; #define LDS_FENCE() asm volatile("s_waitcnt lgkmcnt(0)" ::: "memory")
; template <int EPI> ...
;     ...
;               f32x4 v = acc[h * 4 + mm][n] * rs[h * 4 + mm];
;               if constexpr (EPI == EPI_PROJ) {
;                 if (gate) {
; #pragma unroll
;                   for (int j = 0; j < 4; ++j) v[j] = __builtin_amdgcn_rcpf(1.0f + __expf(-v[j]));
;                 }
;               } else {
; #pragma unroll
;                 for (int j = 0; j < 4; ++j) { float r = fmaxf(v[j], 0.f); v[j] = r * r; }
;               }
;               u32x2 o = {pack2(v[0], v[1]), pack2(v[2], v[3])};
;               *(u32x2*)(wst + (mm * 16 + fr) * 128 + (((n * 2 + (fq >> 1)) ^ wswz) << 4) + (fq & 1) * 8) = o;
;             }
;           LDS_FENCE();
;           if (h == 0) WAIT_V(0);
; #pragma unroll
;           for (int i = 0; i < 8; ++i) {
;             const u32x4 d = *(const u32x4*)(wst + (i * 8 + (lane >> 3)) * 128 + (((lane & 7) ^ rswz) << 4));
;             *(u32x4*)(gout + (long)(h * 64 + i * 8) * ld) = d;
	v_pk_mul_f32 v[104:105], v[104:105], v[150:151] op_sel_hi:[1,0]
	v_pk_mul_f32 v[102:103], v[102:103], v[148:149] op_sel_hi:[1,0]
	v_pk_mul_f32 v[100:101], v[100:101], v[148:149] op_sel_hi:[1,0]
	v_pk_mul_f32 v[94:95], v[98:99], v[148:149] op_sel_hi:[1,0]
	v_pk_mul_f32 v[96:97], v[96:97], v[148:149] op_sel_hi:[1,0]
	v_pk_mul_f32 v[90:91], v[90:91], v[148:149] op_sel_hi:[1,0]
	v_pk_mul_f32 v[88:89], v[88:89], v[148:149] op_sel_hi:[1,0]
	v_pk_mul_f32 v[86:87], v[86:87], v[146:147] op_sel_hi:[1,0]
	v_pk_mul_f32 v[84:85], v[84:85], v[146:147] op_sel_hi:[1,0]
	ds_write2st64_b64 v124, v[92:93], v[76:77] offset0:8 offset1:12
	v_pk_mul_f32 v[76:77], v[82:83], v[146:147] op_sel_hi:[1,0]
	v_pk_mul_f32 v[78:79], v[80:81], v[146:147] op_sel_hi:[1,0]
	v_pk_mul_f32 v[74:75], v[74:75], v[146:147] op_sel_hi:[1,0]
	v_pk_mul_f32 v[72:73], v[72:73], v[146:147] op_sel_hi:[1,0]
	v_pk_mul_f32 v[126:127], v[126:127], v[126:127]
	v_max_f32_e32 v116, 0, v116
	v_max_f32_e32 v117, 0, v117
	v_max_f32_e32 v118, 0, v118
	v_max_f32_e32 v119, 0, v119
	v_max_f32_e32 v110, 0, v110
	v_max_f32_e32 v111, 0, v111
	v_max_f32_e32 v108, 0, v108
	v_max_f32_e32 v109, 0, v109
	v_max_f32_e32 v104, 0, v104
	v_max_f32_e32 v105, 0, v105
	v_max_f32_e32 v106, 0, v106
	v_max_f32_e32 v107, 0, v107
	v_max_f32_e32 v100, 0, v100
	v_max_f32_e32 v101, 0, v101
	v_max_f32_e32 v102, 0, v102
	v_max_f32_e32 v103, 0, v103
	v_max_f32_e32 v96, 0, v96
	v_max_f32_e32 v97, 0, v97
	v_max_f32_e32 v94, 0, v94
	v_max_f32_e32 v95, 0, v95
	v_max_f32_e32 v88, 0, v88
	v_max_f32_e32 v89, 0, v89
	v_max_f32_e32 v90, 0, v90
	v_max_f32_e32 v91, 0, v91
	v_max_f32_e32 v84, 0, v84
	v_max_f32_e32 v85, 0, v85
	v_max_f32_e32 v86, 0, v86
	v_max_f32_e32 v87, 0, v87
	v_max_f32_e32 v78, 0, v78
	v_max_f32_e32 v79, 0, v79
	v_max_f32_e32 v76, 0, v76
	v_max_f32_e32 v77, 0, v77
	v_max_f32_e32 v72, 0, v72
	v_max_f32_e32 v73, 0, v73
	v_max_f32_e32 v74, 0, v74
	v_max_f32_e32 v75, 0, v75
	v_cvt_pk_bf16_f32 v156, v132, v133
	v_bitop3_b32 v132, v149, v141, 7 bitop3:0x78
	v_cvt_pk_bf16_f32 v129, v126, v127
	v_bitop3_b32 v125, v149, v145, 4 bitop3:0x36
	v_cvt_pk_bf16_f32 v126, v120, v121
	v_bitop3_b32 v120, v149, v145, 6 bitop3:0x36
	v_pk_mul_f32 v[116:117], v[116:117], v[116:117]
	v_pk_mul_f32 v[118:119], v[118:119], v[118:119]
	v_pk_mul_f32 v[110:111], v[110:111], v[110:111]
	v_pk_mul_f32 v[108:109], v[108:109], v[108:109]
	v_pk_mul_f32 v[104:105], v[104:105], v[104:105]
	v_pk_mul_f32 v[106:107], v[106:107], v[106:107]
	v_pk_mul_f32 v[100:101], v[100:101], v[100:101]
	v_pk_mul_f32 v[102:103], v[102:103], v[102:103]
	v_pk_mul_f32 v[96:97], v[96:97], v[96:97]
	v_pk_mul_f32 v[94:95], v[94:95], v[94:95]
	v_pk_mul_f32 v[88:89], v[88:89], v[88:89]
	v_pk_mul_f32 v[90:91], v[90:91], v[90:91]
	v_pk_mul_f32 v[84:85], v[84:85], v[84:85]
	v_pk_mul_f32 v[86:87], v[86:87], v[86:87]
	v_pk_mul_f32 v[78:79], v[78:79], v[78:79]
	v_pk_mul_f32 v[76:77], v[76:77], v[76:77]
	v_pk_mul_f32 v[72:73], v[72:73], v[72:73]
	v_pk_mul_f32 v[74:75], v[74:75], v[74:75]
	v_lshl_or_b32 v132, v132, 4, v151
	v_lshl_or_b32 v125, v125, 4, v151
	v_cvt_pk_bf16_f32 v127, v122, v123
	v_lshl_or_b32 v120, v120, 4, v151
	v_cvt_pk_bf16_f32 v116, v116, v117
	v_cvt_pk_bf16_f32 v117, v118, v119
	v_cvt_pk_bf16_f32 v110, v110, v111
	v_cvt_pk_bf16_f32 v111, v108, v109
	v_cvt_pk_bf16_f32 v104, v104, v105
	v_cvt_pk_bf16_f32 v105, v106, v107
	v_cvt_pk_bf16_f32 v100, v100, v101
	v_cvt_pk_bf16_f32 v101, v102, v103
	v_cvt_pk_bf16_f32 v96, v96, v97
	v_cvt_pk_bf16_f32 v97, v94, v95
	v_cvt_pk_bf16_f32 v88, v88, v89
	v_cvt_pk_bf16_f32 v89, v90, v91
	v_cvt_pk_bf16_f32 v84, v84, v85
	v_cvt_pk_bf16_f32 v85, v86, v87
	v_cvt_pk_bf16_f32 v78, v78, v79
	v_cvt_pk_bf16_f32 v79, v76, v77
	v_cvt_pk_bf16_f32 v72, v72, v73
	v_cvt_pk_bf16_f32 v73, v74, v75
	ds_write2st64_b64 v132, v[156:157], v[116:117] offset1:4
	ds_write2st64_b64 v125, v[128:129], v[110:111] offset1:4
	ds_write2st64_b64 v120, v[126:127], v[104:105] offset1:4
	ds_write2st64_b64 v132, v[100:101], v[84:85] offset0:8 offset1:12
	ds_write2st64_b64 v125, v[96:97], v[78:79] offset0:8 offset1:12
	ds_write2st64_b64 v120, v[88:89], v[72:73] offset0:8 offset1:12
	s_waitcnt lgkmcnt(0)
	v_or3_b32 v139, v143, v139, v147
	s_waitcnt vmcnt(0)
	ds_read_b128 v[72:75], v139
	v_add_co_u32_e32 v76, vcc, s68, v136
	s_mov_b32 s20, 0x50000
	s_nop 0
	v_addc_co_u32_e32 v77, vcc, 0, v137, vcc
	s_waitcnt lgkmcnt(0)
	global_store_dwordx4 v[136:137], v[72:75], off
	ds_read_b128 v[72:75], v139 offset:1024
	v_pk_mul_f32 v[70:71], v[70:71], v[144:145] op_sel_hi:[1,0]
	v_pk_mul_f32 v[68:69], v[68:69], v[144:145] op_sel_hi:[1,0]
	v_pk_mul_f32 v[66:67], v[66:67], v[144:145] op_sel_hi:[1,0]
	v_pk_mul_f32 v[64:65], v[64:65], v[144:145] op_sel_hi:[1,0]
	s_waitcnt lgkmcnt(0)
	global_store_dwordx4 v[76:77], v[72:75], off
	ds_read_b128 v[72:75], v139 offset:2048
	v_add_co_u32_e32 v76, vcc, s87, v136
	v_pk_mul_f32 v[62:63], v[62:63], v[144:145] op_sel_hi:[1,0]
	s_nop 0
	v_addc_co_u32_e32 v77, vcc, 0, v137, vcc
	s_waitcnt lgkmcnt(0)
	global_store_dwordx4 v[76:77], v[72:75], off
	ds_read_b128 v[72:75], v139 offset:3072
	v_add_co_u32_e32 v76, vcc, s64, v136
	v_pk_mul_f32 v[60:61], v[60:61], v[144:145] op_sel_hi:[1,0]
	s_nop 0
	v_addc_co_u32_e32 v77, vcc, 0, v137, vcc
	s_waitcnt lgkmcnt(0)
	global_store_dwordx4 v[76:77], v[72:75], off
	ds_read_b128 v[72:75], v139 offset:4096
	v_add_co_u32_e32 v76, vcc, s89, v136
	v_pk_mul_f32 v[58:59], v[58:59], v[144:145] op_sel_hi:[1,0]
	s_nop 0
	v_addc_co_u32_e32 v77, vcc, 0, v137, vcc
	s_waitcnt lgkmcnt(0)
	global_store_dwordx4 v[76:77], v[72:75], off
	ds_read_b128 v[72:75], v139 offset:5120
	v_add_co_u32_e32 v76, vcc, s20, v136
	s_mov_b32 s20, 0x60000
	s_nop 0
	v_addc_co_u32_e32 v77, vcc, 0, v137, vcc
	s_waitcnt lgkmcnt(0)
; #define WAIT_V(n) asm volatile("s_waitcnt vmcnt(%0)" ::"n"(n) : "memory")
; #define LDS_FENCE() asm volatile("s_waitcnt lgkmcnt(0)" ::: "memory")
; template <int EPI> ...
;     ...
;         for (int h = 0; h < 2; ++h) {
; #pragma unroll
;           for (int mm = 0; mm < 4; ++mm)
; #pragma unroll
;             for (int n = 0; n < 4; ++n) {
;               f32x4 v = acc[h * 4 + mm][n] * rs[h * 4 + mm];
;               if constexpr (EPI == EPI_PROJ) {
;                 if (gate) {
; #pragma unroll
;                   for (int j = 0; j < 4; ++j) v[j] = __builtin_amdgcn_rcpf(1.0f + __expf(-v[j]));
;                 }
;               } else {
; #pragma unroll
;                 for (int j = 0; j < 4; ++j) { float r = fmaxf(v[j], 0.f); v[j] = r * r; }
;               }
;               u32x2 o = {pack2(v[0], v[1]), pack2(v[2], v[3])};
;               *(u32x2*)(wst + (mm * 16 + fr) * 128 + (((n * 2 + (fq >> 1)) ^ wswz) << 4) + (fq & 1) * 8) = o;
;             }
;           LDS_FENCE();
;           if (h == 0) WAIT_V(0);
; #pragma unroll
;           for (int i = 0; i < 8; ++i) {
;             const u32x4 d = *(const u32x4*)(wst + (i * 8 + (lane >> 3)) * 128 + (((lane & 7) ^ rswz) << 4));
;             *(u32x4*)(gout + (long)(h * 64 + i * 8) * ld) = d;
	global_store_dwordx4 v[76:77], v[72:75], off
	ds_read_b128 v[72:75], v139 offset:6144
	v_add_co_u32_e32 v76, vcc, s20, v136
	s_mov_b32 s20, 0x70000
	s_nop 0
	v_addc_co_u32_e32 v77, vcc, 0, v137, vcc
	s_waitcnt lgkmcnt(0)
	global_store_dwordx4 v[76:77], v[72:75], off
	ds_read_b128 v[72:75], v139 offset:7168
	v_pk_mul_f32 v[56:57], v[56:57], v[144:145] op_sel_hi:[1,0]
	v_pk_mul_f32 v[54:55], v[54:55], v[142:143] op_sel_hi:[1,0]
	v_pk_mul_f32 v[52:53], v[52:53], v[142:143] op_sel_hi:[1,0]
	v_pk_mul_f32 v[50:51], v[50:51], v[142:143] op_sel_hi:[1,0]
	v_pk_mul_f32 v[48:49], v[48:49], v[142:143] op_sel_hi:[1,0]
	v_pk_mul_f32 v[46:47], v[46:47], v[142:143] op_sel_hi:[1,0]
	v_pk_mul_f32 v[44:45], v[44:45], v[142:143] op_sel_hi:[1,0]
	v_pk_mul_f32 v[42:43], v[42:43], v[142:143] op_sel_hi:[1,0]
	v_pk_mul_f32 v[40:41], v[40:41], v[142:143] op_sel_hi:[1,0]
	v_pk_mul_f32 v[38:39], v[38:39], v[140:141] op_sel_hi:[1,0]
	v_pk_mul_f32 v[36:37], v[36:37], v[140:141] op_sel_hi:[1,0]
	v_pk_mul_f32 v[34:35], v[34:35], v[140:141] op_sel_hi:[1,0]
	v_pk_mul_f32 v[32:33], v[32:33], v[140:141] op_sel_hi:[1,0]
	v_pk_mul_f32 v[30:31], v[30:31], v[140:141] op_sel_hi:[1,0]
	v_pk_mul_f32 v[28:29], v[28:29], v[140:141] op_sel_hi:[1,0]
	v_pk_mul_f32 v[26:27], v[26:27], v[140:141] op_sel_hi:[1,0]
	v_pk_mul_f32 v[24:25], v[24:25], v[140:141] op_sel_hi:[1,0]
	v_pk_mul_f32 v[22:23], v[22:23], v[138:139] op_sel_hi:[1,0]
	v_pk_mul_f32 v[20:21], v[20:21], v[138:139] op_sel_hi:[1,0]
	v_pk_mul_f32 v[18:19], v[18:19], v[138:139] op_sel_hi:[1,0]
	v_pk_mul_f32 v[16:17], v[16:17], v[138:139] op_sel_hi:[1,0]
	v_pk_mul_f32 v[14:15], v[14:15], v[138:139] op_sel_hi:[1,0]
	v_pk_mul_f32 v[12:13], v[12:13], v[138:139] op_sel_hi:[1,0]
	v_pk_mul_f32 v[10:11], v[10:11], v[138:139] op_sel_hi:[1,0]
	v_pk_mul_f32 v[8:9], v[8:9], v[138:139] op_sel_hi:[1,0]
	v_add_co_u32_e32 v76, vcc, s20, v136
	v_max_f32_e32 v68, 0, v68
	v_max_f32_e32 v69, 0, v69
	v_max_f32_e32 v70, 0, v70
	v_max_f32_e32 v71, 0, v71
	v_max_f32_e32 v64, 0, v64
	v_max_f32_e32 v65, 0, v65
	v_max_f32_e32 v66, 0, v66
	v_max_f32_e32 v67, 0, v67
	v_max_f32_e32 v60, 0, v60
	v_max_f32_e32 v61, 0, v61
	v_max_f32_e32 v62, 0, v62
	v_max_f32_e32 v63, 0, v63
	v_max_f32_e32 v56, 0, v56
	v_max_f32_e32 v57, 0, v57
	v_max_f32_e32 v58, 0, v58
	v_max_f32_e32 v59, 0, v59
	v_max_f32_e32 v52, 0, v52
	v_max_f32_e32 v53, 0, v53
	v_max_f32_e32 v54, 0, v54
	v_max_f32_e32 v55, 0, v55
	v_max_f32_e32 v48, 0, v48
	v_max_f32_e32 v49, 0, v49
	v_max_f32_e32 v50, 0, v50
	v_max_f32_e32 v51, 0, v51
	v_max_f32_e32 v44, 0, v44
	v_max_f32_e32 v45, 0, v45
	v_max_f32_e32 v46, 0, v46
	v_max_f32_e32 v47, 0, v47
	v_max_f32_e32 v40, 0, v40
	v_max_f32_e32 v41, 0, v41
	v_max_f32_e32 v42, 0, v42
	v_max_f32_e32 v43, 0, v43
	v_max_f32_e32 v36, 0, v36
	v_max_f32_e32 v37, 0, v37
	v_max_f32_e32 v38, 0, v38
	v_max_f32_e32 v39, 0, v39
	v_max_f32_e32 v32, 0, v32
	v_max_f32_e32 v33, 0, v33
	v_max_f32_e32 v34, 0, v34
	v_max_f32_e32 v35, 0, v35
	v_max_f32_e32 v28, 0, v28
	v_max_f32_e32 v29, 0, v29
	v_max_f32_e32 v30, 0, v30
	v_max_f32_e32 v31, 0, v31
	v_max_f32_e32 v24, 0, v24
	v_max_f32_e32 v25, 0, v25
	v_max_f32_e32 v26, 0, v26
	v_max_f32_e32 v27, 0, v27
	v_max_f32_e32 v20, 0, v20
	v_max_f32_e32 v21, 0, v21
	v_max_f32_e32 v22, 0, v22
	v_max_f32_e32 v23, 0, v23
	v_max_f32_e32 v16, 0, v16
	v_max_f32_e32 v17, 0, v17
	v_max_f32_e32 v18, 0, v18
	v_max_f32_e32 v19, 0, v19
	v_max_f32_e32 v12, 0, v12
	v_max_f32_e32 v13, 0, v13
	v_max_f32_e32 v14, 0, v14
	v_max_f32_e32 v15, 0, v15
	v_max_f32_e32 v8, 0, v8
	v_max_f32_e32 v9, 0, v9
	v_max_f32_e32 v10, 0, v10
	v_max_f32_e32 v11, 0, v11
	v_addc_co_u32_e32 v77, vcc, 0, v137, vcc
	v_pk_mul_f32 v[68:69], v[68:69], v[68:69]
	v_pk_mul_f32 v[70:71], v[70:71], v[70:71]
	v_pk_mul_f32 v[64:65], v[64:65], v[64:65]
	v_pk_mul_f32 v[66:67], v[66:67], v[66:67]
	v_pk_mul_f32 v[60:61], v[60:61], v[60:61]
	v_pk_mul_f32 v[62:63], v[62:63], v[62:63]
	v_pk_mul_f32 v[56:57], v[56:57], v[56:57]
	v_pk_mul_f32 v[58:59], v[58:59], v[58:59]
	v_pk_mul_f32 v[52:53], v[52:53], v[52:53]
	v_pk_mul_f32 v[54:55], v[54:55], v[54:55]
	v_pk_mul_f32 v[48:49], v[48:49], v[48:49]
	v_pk_mul_f32 v[50:51], v[50:51], v[50:51]
	v_pk_mul_f32 v[44:45], v[44:45], v[44:45]
	v_pk_mul_f32 v[46:47], v[46:47], v[46:47]
	v_pk_mul_f32 v[40:41], v[40:41], v[40:41]
	v_pk_mul_f32 v[42:43], v[42:43], v[42:43]
	v_pk_mul_f32 v[36:37], v[36:37], v[36:37]
	v_pk_mul_f32 v[38:39], v[38:39], v[38:39]
	v_pk_mul_f32 v[32:33], v[32:33], v[32:33]
	v_pk_mul_f32 v[34:35], v[34:35], v[34:35]
	v_pk_mul_f32 v[28:29], v[28:29], v[28:29]
	v_pk_mul_f32 v[30:31], v[30:31], v[30:31]
	v_pk_mul_f32 v[24:25], v[24:25], v[24:25]
	v_pk_mul_f32 v[26:27], v[26:27], v[26:27]
	v_pk_mul_f32 v[20:21], v[20:21], v[20:21]
	v_pk_mul_f32 v[22:23], v[22:23], v[22:23]
	v_pk_mul_f32 v[16:17], v[16:17], v[16:17]
	v_pk_mul_f32 v[18:19], v[18:19], v[18:19]
	v_pk_mul_f32 v[12:13], v[12:13], v[12:13]
	v_pk_mul_f32 v[14:15], v[14:15], v[14:15]
	v_pk_mul_f32 v[8:9], v[8:9], v[8:9]
	v_pk_mul_f32 v[10:11], v[10:11], v[10:11]
	s_waitcnt lgkmcnt(0)
; #define WAIT_V(n) asm volatile("s_waitcnt vmcnt(%0)" ::"n"(n) : "memory")
; #define RAW_BARRIER()                                     \
;   do {                                                    \
;     asm volatile("s_waitcnt lgkmcnt(0)" ::: "memory");    \
;     __builtin_amdgcn_s_barrier();                         \
;   } while (0)
; #define LDS_FENCE() asm volatile("s_waitcnt lgkmcnt(0)" ::: "memory")
; template <int EPI> ...
;     ...
;               u32x2 o = {pack2(v[0], v[1]), pack2(v[2], v[3])};
;               *(u32x2*)(wst + (mm * 16 + fr) * 128 + (((n * 2 + (fq >> 1)) ^ wswz) << 4) + (fq & 1) * 8) = o;
;             }
;           LDS_FENCE();
;           if (h == 0) WAIT_V(0);
; #pragma unroll
;           for (int i = 0; i < 8; ++i) {
;             const u32x4 d = *(const u32x4*)(wst + (i * 8 + (lane >> 3)) * 128 + (((lane & 7) ^ rswz) << 4));
;             *(u32x4*)(gout + (long)(h * 64 + i * 8) * ld) = d;
;           }
;           LDS_FENCE();
;         }
;     ...
;     RAW_BARRIER();
	global_store_dwordx4 v[76:77], v[72:75], off
	v_cvt_pk_bf16_f32 v68, v68, v69
	v_cvt_pk_bf16_f32 v69, v70, v71
	v_cvt_pk_bf16_f32 v64, v64, v65
	v_cvt_pk_bf16_f32 v65, v66, v67
	v_cvt_pk_bf16_f32 v60, v60, v61
	v_cvt_pk_bf16_f32 v61, v62, v63
	v_cvt_pk_bf16_f32 v56, v56, v57
	v_cvt_pk_bf16_f32 v57, v58, v59
	v_cvt_pk_bf16_f32 v52, v52, v53
	v_cvt_pk_bf16_f32 v53, v54, v55
	v_cvt_pk_bf16_f32 v48, v48, v49
	v_cvt_pk_bf16_f32 v49, v50, v51
	v_cvt_pk_bf16_f32 v44, v44, v45
	v_cvt_pk_bf16_f32 v45, v46, v47
	v_cvt_pk_bf16_f32 v40, v40, v41
	v_cvt_pk_bf16_f32 v41, v42, v43
	v_cvt_pk_bf16_f32 v36, v36, v37
	v_cvt_pk_bf16_f32 v37, v38, v39
	v_cvt_pk_bf16_f32 v32, v32, v33
	v_cvt_pk_bf16_f32 v33, v34, v35
	v_cvt_pk_bf16_f32 v28, v28, v29
	v_cvt_pk_bf16_f32 v29, v30, v31
	v_cvt_pk_bf16_f32 v24, v24, v25
	v_cvt_pk_bf16_f32 v25, v26, v27
	v_cvt_pk_bf16_f32 v20, v20, v21
	v_cvt_pk_bf16_f32 v21, v22, v23
	v_cvt_pk_bf16_f32 v16, v16, v17
	v_cvt_pk_bf16_f32 v17, v18, v19
	v_cvt_pk_bf16_f32 v12, v12, v13
	v_cvt_pk_bf16_f32 v13, v14, v15
	v_cvt_pk_bf16_f32 v8, v8, v9
	v_cvt_pk_bf16_f32 v9, v10, v11
	s_waitcnt lgkmcnt(0)
	ds_write2st64_b64 v132, v[68:69], v[52:53] offset1:4
	ds_write2st64_b64 v124, v[64:65], v[48:49] offset1:4
	ds_write2st64_b64 v125, v[60:61], v[44:45] offset1:4
	ds_write2st64_b64 v120, v[56:57], v[40:41] offset1:4
	ds_write2st64_b64 v132, v[36:37], v[20:21] offset0:8 offset1:12
	ds_write2st64_b64 v124, v[32:33], v[16:17] offset0:8 offset1:12
	ds_write2st64_b64 v125, v[28:29], v[12:13] offset0:8 offset1:12
	ds_write2st64_b64 v120, v[24:25], v[8:9] offset0:8 offset1:12
	s_waitcnt lgkmcnt(0)
	ds_read_b128 v[8:11], v139
	s_mov_b32 s20, 0x80000
	v_add_co_u32_e32 v12, vcc, s20, v136
	s_mov_b32 s20, 0x90000
	s_nop 0
	v_addc_co_u32_e32 v13, vcc, 0, v137, vcc
	s_waitcnt lgkmcnt(0)
	global_store_dwordx4 v[12:13], v[8:11], off
	ds_read_b128 v[8:11], v139 offset:1024
	v_add_co_u32_e32 v12, vcc, s20, v136
	s_mov_b32 s20, 0xa0000
	s_nop 0
	v_addc_co_u32_e32 v13, vcc, 0, v137, vcc
	s_waitcnt lgkmcnt(0)
	global_store_dwordx4 v[12:13], v[8:11], off
	ds_read_b128 v[8:11], v139 offset:2048
	v_add_co_u32_e32 v12, vcc, s20, v136
	s_mov_b32 s20, 0xb0000
	s_nop 0
	v_addc_co_u32_e32 v13, vcc, 0, v137, vcc
	s_waitcnt lgkmcnt(0)
	global_store_dwordx4 v[12:13], v[8:11], off
	ds_read_b128 v[8:11], v139 offset:3072
	v_add_co_u32_e32 v12, vcc, s20, v136
	s_mov_b32 s20, 0xc0000
	s_nop 0
	v_addc_co_u32_e32 v13, vcc, 0, v137, vcc
	s_waitcnt lgkmcnt(0)
	global_store_dwordx4 v[12:13], v[8:11], off
	ds_read_b128 v[8:11], v139 offset:4096
	v_add_co_u32_e32 v12, vcc, s20, v136
	s_mov_b32 s20, 0xd0000
	s_nop 0
	v_addc_co_u32_e32 v13, vcc, 0, v137, vcc
	s_waitcnt lgkmcnt(0)
	global_store_dwordx4 v[12:13], v[8:11], off
	ds_read_b128 v[8:11], v139 offset:5120
	v_add_co_u32_e32 v12, vcc, s20, v136
	s_mov_b64 s[22:23], s[16:17]
	s_nop 0
	v_addc_co_u32_e32 v13, vcc, 0, v137, vcc
	s_waitcnt lgkmcnt(0)
	global_store_dwordx4 v[12:13], v[8:11], off
	ds_read_b128 v[8:11], v139 offset:6144
	v_add_co_u32_e32 v12, vcc, 0xe0000, v136
	s_nop 1
	v_addc_co_u32_e32 v13, vcc, 0, v137, vcc
	s_waitcnt lgkmcnt(0)
	global_store_dwordx4 v[12:13], v[8:11], off
	ds_read_b128 v[8:11], v139 offset:7168
	v_add_co_u32_e32 v12, vcc, 0xf0000, v136
	s_nop 1
	v_addc_co_u32_e32 v13, vcc, 0, v137, vcc
	s_waitcnt lgkmcnt(0)
	global_store_dwordx4 v[12:13], v[8:11], off
	s_waitcnt lgkmcnt(0)
	s_waitcnt lgkmcnt(0)
	s_andn2_b64 vcc, exec, s[4:5]
	s_barrier
	s_cbranch_vccz .LBB0_691
